# final RMSNorm phase software-pipelined: norm weights loaded once, next row loads issued before the current row is reduced, waits no longer drain stores
# speedup vs baseline: 1.0175x; 1.0005x over previous
.LBB0_1923:
	s_or_b64 exec, exec, s[0:1]
	s_and_b64 vcc, exec, s[54:55]
	s_waitcnt lgkmcnt(0)
	s_barrier
	s_cbranch_vccnz .LBB0_1926
	v_mbcnt_hi_u32_b32 v2, -1, v221
	v_and_b32_e32 v0, 64, v2
	s_lshl_b32 s0, s2, 2
	s_lshl_b32 s1, s74, 2
	v_mov_b32_e32 v1, 0
	v_add_u32_e32 v3, 64, v0
	s_waitcnt vmcnt(48)
	v_xor_b32_e32 v4, 32, v2
	v_xor_b32_e32 v5, 16, v2
	v_xor_b32_e32 v6, 8, v2
	v_xor_b32_e32 v7, 4, v2
	v_xor_b32_e32 v8, 2, v2
	v_xor_b32_e32 v9, 1, v2
	v_mov_b32_e32 v10, 0x358637bd
	s_mov_b32 s3, 0x800000
	s_waitcnt vmcnt(0)
	v_lshlrev_b32_e32 v0, 4, v220
	v_and_b32_e32 v0, 0x3f0, v0
	v_ashrrev_i32_e32 v55, 6, v220
	global_load_dwordx4 v[56:59], v0, s[68:69]
	global_load_dwordx4 v[60:63], v0, s[68:69] offset:1024
	global_load_dwordx4 v[64:67], v0, s[68:69] offset:2048
	global_load_dwordx4 v[68:71], v0, s[68:69] offset:3072
	v_cmp_lt_i32_e32 vcc, v4, v3
	v_cndmask_b32_e32 v90, v2, v4, vcc
	v_lshlrev_b32_e32 v90, 2, v90
	v_cmp_lt_i32_e32 vcc, v5, v3
	v_cndmask_b32_e32 v50, v2, v5, vcc
	v_lshlrev_b32_e32 v50, 2, v50
	v_cmp_lt_i32_e32 vcc, v6, v3
	v_cndmask_b32_e32 v51, v2, v6, vcc
	v_lshlrev_b32_e32 v51, 2, v51
	v_cmp_lt_i32_e32 vcc, v7, v3
	v_cndmask_b32_e32 v52, v2, v7, vcc
	v_lshlrev_b32_e32 v52, 2, v52
	v_cmp_lt_i32_e32 vcc, v8, v3
	v_cndmask_b32_e32 v53, v2, v8, vcc
	v_lshlrev_b32_e32 v53, 2, v53
	v_cmp_lt_i32_e32 vcc, v9, v3
	v_cndmask_b32_e32 v54, v2, v9, vcc
	v_lshlrev_b32_e32 v54, 2, v54
	v_add_u32_e32 v12, s0, v55
	v_ashrrev_i32_e32 v13, 31, v12
	v_lshlrev_b64 v[12:13], 12, v[12:13]
	v_lshl_add_u64 v[12:13], s[70:71], 0, v[12:13]
	v_lshl_add_u64 v[32:33], v[12:13], 0, v[0:1]
	global_load_dwordx4 v[12:15], v[32:33], off nt
	global_load_dwordx4 v[16:19], v[32:33], off offset:1024 nt
	global_load_dwordx4 v[20:23], v[32:33], off offset:2048 nt
	global_load_dwordx4 v[24:27], v[32:33], off offset:3072 nt
	s_add_i32 s4, s0, s1
	s_min_i32 s4, s4, 0x7ffc
	v_add_u32_e32 v72, s4, v55
	v_ashrrev_i32_e32 v73, 31, v72
	v_lshlrev_b64 v[72:73], 12, v[72:73]
	v_lshl_add_u64 v[72:73], s[70:71], 0, v[72:73]
	v_lshl_add_u64 v[88:89], v[72:73], 0, v[0:1]
	global_load_dwordx4 v[72:75], v[88:89], off nt
	global_load_dwordx4 v[76:79], v[88:89], off offset:1024 nt
	global_load_dwordx4 v[80:83], v[88:89], off offset:2048 nt
	global_load_dwordx4 v[84:87], v[88:89], off offset:3072 nt
	s_waitcnt vmcnt(4)
	v_mov_b32_e32 v36, v13
	v_mov_b32_e32 v37, v17
	v_mov_b32_e32 v35, v16
	v_mov_b32_e32 v34, v12
	v_mov_b32_e32 v44, v21
	v_mov_b32_e32 v45, v25
	v_pk_mul_f32 v[36:37], v[36:37], v[36:37]
	v_mov_b32_e32 v38, v14
	v_mov_b32_e32 v39, v18
	v_mov_b32_e32 v42, v20
	v_mov_b32_e32 v43, v24
	v_pk_mul_f32 v[44:45], v[44:45], v[44:45]
	v_pk_fma_f32 v[34:35], v[34:35], v[34:35], v[36:37]
	v_mov_b32_e32 v40, v15
	v_mov_b32_e32 v41, v19
	v_mov_b32_e32 v46, v22
	v_mov_b32_e32 v47, v26
	v_pk_fma_f32 v[36:37], v[42:43], v[42:43], v[44:45]
	v_pk_fma_f32 v[34:35], v[38:39], v[38:39], v[34:35]
	v_mov_b32_e32 v48, v23
	v_mov_b32_e32 v49, v27
	v_pk_fma_f32 v[36:37], v[46:47], v[46:47], v[36:37]
	v_pk_fma_f32 v[34:35], v[40:41], v[40:41], v[34:35]
	v_pk_fma_f32 v[36:37], v[48:49], v[48:49], v[36:37]
	v_add_f32_e32 v34, v34, v35
	v_add_f32_e32 v34, v34, v36
	v_add_f32_e32 v34, v34, v37
	ds_bpermute_b32 v91, v90, v34
	s_waitcnt lgkmcnt(0)
	v_add_f32_e32 v11, v34, v91
	ds_bpermute_b32 v34, v50, v11
	s_waitcnt lgkmcnt(0)
	v_add_f32_e32 v11, v11, v34
	ds_bpermute_b32 v34, v51, v11
	s_waitcnt lgkmcnt(0)
	v_add_f32_e32 v11, v11, v34
	ds_bpermute_b32 v34, v52, v11
	s_waitcnt lgkmcnt(0)
	v_add_f32_e32 v11, v11, v34
	ds_bpermute_b32 v34, v53, v11
	s_waitcnt lgkmcnt(0)
	v_add_f32_e32 v11, v11, v34
	ds_bpermute_b32 v34, v54, v11
	s_waitcnt lgkmcnt(0)
	v_add_f32_e32 v11, v11, v34
	v_fmamk_f32 v11, v11, 0x3a800000, v10
	v_mul_f32_e32 v34, 0x4b800000, v11
	v_cmp_gt_f32_e32 vcc, s3, v11
	s_nop 1
	v_cndmask_b32_e32 v11, v11, v34, vcc
	v_rsq_f32_e32 v11, v11
	s_nop 0
	v_mul_f32_e32 v34, 0x45800000, v11
	v_cndmask_b32_e32 v34, v11, v34, vcc
	v_pk_mul_f32 v[12:13], v[12:13], v[34:35] op_sel_hi:[1,0]
	v_pk_mul_f32 v[14:15], v[14:15], v[34:35] op_sel_hi:[1,0]
	v_pk_mul_f32 v[12:13], v[56:57], v[12:13]
	v_pk_mul_f32 v[14:15], v[58:59], v[14:15]
	global_store_dwordx4 v[32:33], v[12:15], off nt
	v_pk_mul_f32 v[16:17], v[16:17], v[34:35] op_sel_hi:[1,0]
	v_pk_mul_f32 v[18:19], v[18:19], v[34:35] op_sel_hi:[1,0]
	v_pk_mul_f32 v[16:17], v[60:61], v[16:17]
	v_pk_mul_f32 v[18:19], v[62:63], v[18:19]
	global_store_dwordx4 v[32:33], v[16:19], off offset:1024 nt
	v_pk_mul_f32 v[20:21], v[20:21], v[34:35] op_sel_hi:[1,0]
	v_pk_mul_f32 v[22:23], v[22:23], v[34:35] op_sel_hi:[1,0]
	v_pk_mul_f32 v[20:21], v[64:65], v[20:21]
	v_pk_mul_f32 v[22:23], v[66:67], v[22:23]
	global_store_dwordx4 v[32:33], v[20:23], off offset:2048 nt
	v_pk_mul_f32 v[24:25], v[24:25], v[34:35] op_sel_hi:[1,0]
	v_pk_mul_f32 v[26:27], v[26:27], v[34:35] op_sel_hi:[1,0]
	v_pk_mul_f32 v[24:25], v[68:69], v[24:25]
	v_pk_mul_f32 v[26:27], v[70:71], v[26:27]
	global_store_dwordx4 v[32:33], v[24:27], off offset:3072 nt
	s_add_i32 s2, s2, s74
	s_add_i32 s0, s0, s1
	s_cmpk_lt_i32 s2, 0x2000
	s_cbranch_scc0 .Lfn_done
.Lfn_loop:
	s_add_i32 s4, s0, s1
	s_min_i32 s4, s4, 0x7ffc
	v_add_u32_e32 v12, s4, v55
	v_ashrrev_i32_e32 v13, 31, v12
	v_lshlrev_b64 v[12:13], 12, v[12:13]
	v_lshl_add_u64 v[12:13], s[70:71], 0, v[12:13]
	v_lshl_add_u64 v[32:33], v[12:13], 0, v[0:1]
	global_load_dwordx4 v[12:15], v[32:33], off nt
	global_load_dwordx4 v[16:19], v[32:33], off offset:1024 nt
	global_load_dwordx4 v[20:23], v[32:33], off offset:2048 nt
	global_load_dwordx4 v[24:27], v[32:33], off offset:3072 nt
	s_waitcnt vmcnt(8)
	v_mov_b32_e32 v36, v73
	v_mov_b32_e32 v37, v77
	v_mov_b32_e32 v35, v76
	v_mov_b32_e32 v34, v72
	v_mov_b32_e32 v44, v81
	v_mov_b32_e32 v45, v85
	v_pk_mul_f32 v[36:37], v[36:37], v[36:37]
	v_mov_b32_e32 v38, v74
	v_mov_b32_e32 v39, v78
	v_mov_b32_e32 v42, v80
	v_mov_b32_e32 v43, v84
	v_pk_mul_f32 v[44:45], v[44:45], v[44:45]
	v_pk_fma_f32 v[34:35], v[34:35], v[34:35], v[36:37]
	v_mov_b32_e32 v40, v75
	v_mov_b32_e32 v41, v79
	v_mov_b32_e32 v46, v82
	v_mov_b32_e32 v47, v86
	v_pk_fma_f32 v[36:37], v[42:43], v[42:43], v[44:45]
	v_pk_fma_f32 v[34:35], v[38:39], v[38:39], v[34:35]
	v_mov_b32_e32 v48, v83
	v_mov_b32_e32 v49, v87
	v_pk_fma_f32 v[36:37], v[46:47], v[46:47], v[36:37]
	v_pk_fma_f32 v[34:35], v[40:41], v[40:41], v[34:35]
	v_pk_fma_f32 v[36:37], v[48:49], v[48:49], v[36:37]
	v_add_f32_e32 v34, v34, v35
	v_add_f32_e32 v34, v34, v36
	v_add_f32_e32 v34, v34, v37
	ds_bpermute_b32 v91, v90, v34
	s_waitcnt lgkmcnt(0)
	v_add_f32_e32 v11, v34, v91
	ds_bpermute_b32 v34, v50, v11
	s_waitcnt lgkmcnt(0)
	v_add_f32_e32 v11, v11, v34
	ds_bpermute_b32 v34, v51, v11
	s_waitcnt lgkmcnt(0)
	v_add_f32_e32 v11, v11, v34
	ds_bpermute_b32 v34, v52, v11
	s_waitcnt lgkmcnt(0)
	v_add_f32_e32 v11, v11, v34
	ds_bpermute_b32 v34, v53, v11
	s_waitcnt lgkmcnt(0)
	v_add_f32_e32 v11, v11, v34
	ds_bpermute_b32 v34, v54, v11
	s_waitcnt lgkmcnt(0)
	v_add_f32_e32 v11, v11, v34
	v_fmamk_f32 v11, v11, 0x3a800000, v10
	v_mul_f32_e32 v34, 0x4b800000, v11
	v_cmp_gt_f32_e32 vcc, s3, v11
	s_nop 1
	v_cndmask_b32_e32 v11, v11, v34, vcc
	v_rsq_f32_e32 v11, v11
	s_nop 0
	v_mul_f32_e32 v34, 0x45800000, v11
	v_cndmask_b32_e32 v34, v11, v34, vcc
	v_pk_mul_f32 v[72:73], v[72:73], v[34:35] op_sel_hi:[1,0]
	v_pk_mul_f32 v[74:75], v[74:75], v[34:35] op_sel_hi:[1,0]
	v_pk_mul_f32 v[72:73], v[56:57], v[72:73]
	v_pk_mul_f32 v[74:75], v[58:59], v[74:75]
	global_store_dwordx4 v[88:89], v[72:75], off nt
	v_pk_mul_f32 v[76:77], v[76:77], v[34:35] op_sel_hi:[1,0]
	v_pk_mul_f32 v[78:79], v[78:79], v[34:35] op_sel_hi:[1,0]
	v_pk_mul_f32 v[76:77], v[60:61], v[76:77]
	v_pk_mul_f32 v[78:79], v[62:63], v[78:79]
	global_store_dwordx4 v[88:89], v[76:79], off offset:1024 nt
	v_pk_mul_f32 v[80:81], v[80:81], v[34:35] op_sel_hi:[1,0]
	v_pk_mul_f32 v[82:83], v[82:83], v[34:35] op_sel_hi:[1,0]
	v_pk_mul_f32 v[80:81], v[64:65], v[80:81]
	v_pk_mul_f32 v[82:83], v[66:67], v[82:83]
	global_store_dwordx4 v[88:89], v[80:83], off offset:2048 nt
	v_pk_mul_f32 v[84:85], v[84:85], v[34:35] op_sel_hi:[1,0]
	v_pk_mul_f32 v[86:87], v[86:87], v[34:35] op_sel_hi:[1,0]
	v_pk_mul_f32 v[84:85], v[68:69], v[84:85]
	v_pk_mul_f32 v[86:87], v[70:71], v[86:87]
	global_store_dwordx4 v[88:89], v[84:87], off offset:3072 nt
	s_add_i32 s2, s2, s74
	s_add_i32 s0, s0, s1
	s_cmpk_lt_i32 s2, 0x2000
	s_cbranch_scc0 .Lfn_done
	s_add_i32 s4, s0, s1
	s_min_i32 s4, s4, 0x7ffc
	v_add_u32_e32 v72, s4, v55
	v_ashrrev_i32_e32 v73, 31, v72
	v_lshlrev_b64 v[72:73], 12, v[72:73]
	v_lshl_add_u64 v[72:73], s[70:71], 0, v[72:73]
	v_lshl_add_u64 v[88:89], v[72:73], 0, v[0:1]
	global_load_dwordx4 v[72:75], v[88:89], off nt
	global_load_dwordx4 v[76:79], v[88:89], off offset:1024 nt
	global_load_dwordx4 v[80:83], v[88:89], off offset:2048 nt
	global_load_dwordx4 v[84:87], v[88:89], off offset:3072 nt
	s_waitcnt vmcnt(8)
	v_mov_b32_e32 v36, v13
	v_mov_b32_e32 v37, v17
	v_mov_b32_e32 v35, v16
	v_mov_b32_e32 v34, v12
	v_mov_b32_e32 v44, v21
	v_mov_b32_e32 v45, v25
	v_pk_mul_f32 v[36:37], v[36:37], v[36:37]
	v_mov_b32_e32 v38, v14
	v_mov_b32_e32 v39, v18
	v_mov_b32_e32 v42, v20
	v_mov_b32_e32 v43, v24
	v_pk_mul_f32 v[44:45], v[44:45], v[44:45]
	v_pk_fma_f32 v[34:35], v[34:35], v[34:35], v[36:37]
	v_mov_b32_e32 v40, v15
	v_mov_b32_e32 v41, v19
	v_mov_b32_e32 v46, v22
	v_mov_b32_e32 v47, v26
	v_pk_fma_f32 v[36:37], v[42:43], v[42:43], v[44:45]
	v_pk_fma_f32 v[34:35], v[38:39], v[38:39], v[34:35]
	v_mov_b32_e32 v48, v23
	v_mov_b32_e32 v49, v27
	v_pk_fma_f32 v[36:37], v[46:47], v[46:47], v[36:37]
	v_pk_fma_f32 v[34:35], v[40:41], v[40:41], v[34:35]
	v_pk_fma_f32 v[36:37], v[48:49], v[48:49], v[36:37]
	v_add_f32_e32 v34, v34, v35
	v_add_f32_e32 v34, v34, v36
	v_add_f32_e32 v34, v34, v37
	ds_bpermute_b32 v91, v90, v34
	s_waitcnt lgkmcnt(0)
	v_add_f32_e32 v11, v34, v91
	ds_bpermute_b32 v34, v50, v11
	s_waitcnt lgkmcnt(0)
	v_add_f32_e32 v11, v11, v34
	ds_bpermute_b32 v34, v51, v11
	s_waitcnt lgkmcnt(0)
	v_add_f32_e32 v11, v11, v34
	ds_bpermute_b32 v34, v52, v11
	s_waitcnt lgkmcnt(0)
	v_add_f32_e32 v11, v11, v34
	ds_bpermute_b32 v34, v53, v11
	s_waitcnt lgkmcnt(0)
	v_add_f32_e32 v11, v11, v34
	ds_bpermute_b32 v34, v54, v11
	s_waitcnt lgkmcnt(0)
	v_add_f32_e32 v11, v11, v34
	v_fmamk_f32 v11, v11, 0x3a800000, v10
	v_mul_f32_e32 v34, 0x4b800000, v11
	v_cmp_gt_f32_e32 vcc, s3, v11
	s_nop 1
	v_cndmask_b32_e32 v11, v11, v34, vcc
	v_rsq_f32_e32 v11, v11
	s_nop 0
	v_mul_f32_e32 v34, 0x45800000, v11
	v_cndmask_b32_e32 v34, v11, v34, vcc
	v_pk_mul_f32 v[12:13], v[12:13], v[34:35] op_sel_hi:[1,0]
	v_pk_mul_f32 v[14:15], v[14:15], v[34:35] op_sel_hi:[1,0]
	v_pk_mul_f32 v[12:13], v[56:57], v[12:13]
	v_pk_mul_f32 v[14:15], v[58:59], v[14:15]
	global_store_dwordx4 v[32:33], v[12:15], off nt
	v_pk_mul_f32 v[16:17], v[16:17], v[34:35] op_sel_hi:[1,0]
	v_pk_mul_f32 v[18:19], v[18:19], v[34:35] op_sel_hi:[1,0]
	v_pk_mul_f32 v[16:17], v[60:61], v[16:17]
	v_pk_mul_f32 v[18:19], v[62:63], v[18:19]
	global_store_dwordx4 v[32:33], v[16:19], off offset:1024 nt
	v_pk_mul_f32 v[20:21], v[20:21], v[34:35] op_sel_hi:[1,0]
	v_pk_mul_f32 v[22:23], v[22:23], v[34:35] op_sel_hi:[1,0]
	v_pk_mul_f32 v[20:21], v[64:65], v[20:21]
	v_pk_mul_f32 v[22:23], v[66:67], v[22:23]
	global_store_dwordx4 v[32:33], v[20:23], off offset:2048 nt
	v_pk_mul_f32 v[24:25], v[24:25], v[34:35] op_sel_hi:[1,0]
	v_pk_mul_f32 v[26:27], v[26:27], v[34:35] op_sel_hi:[1,0]
	v_pk_mul_f32 v[24:25], v[68:69], v[24:25]
	v_pk_mul_f32 v[26:27], v[70:71], v[26:27]
	global_store_dwordx4 v[32:33], v[24:27], off offset:3072 nt
	s_add_i32 s2, s2, s74
	s_add_i32 s0, s0, s1
	s_cmpk_lt_i32 s2, 0x2000
	s_cbranch_scc1 .Lfn_loop
.Lfn_done:
.LBB0_1926:
	s_endpgm
